# attention tile loop: four LDS operand reads kept in flight ahead of the MFMAs with counted lgkmcnt waits
# baseline (speedup 1.0000x reference)
.LBB0_541:
	v_mov_b32_e32 v0, v147
	s_add_i32 s6, s15, 64
	v_ashrrev_i32_e32 v68, 3, v0
	v_and_b32_e32 v69, 7, v0
	v_lshlrev_b32_e32 v66, 4, v0
	v_lshlrev_b32_e32 v0, 3, v0
	v_and_b32_e32 v66, 64, v66
	v_and_b32_e32 v0, 24, v0
	v_mul_lo_u32 v67, v68, s43
	v_or3_b32 v0, v0, v66, v67
	v_lshl_add_u64 v[66:67], v[0:1], 1, s[40:41]
	s_lshl_b64 s[40:41], s[80:81], 1
	s_add_u32 s40, s45, s40
	s_mov_b32 s7, s81
	s_addc_u32 s41, s94, s41
	s_lshl_b64 s[6:7], s[6:7], 1
	s_add_u32 s43, s69, s6
	s_addc_u32 s76, s72, s7
	s_and_b64 s[6:7], exec, s[38:39]
	s_cselect_b32 s6, s76, s41
	s_cselect_b32 s7, s43, s40
	v_mul_lo_u32 v0, v68, s42
	global_load_dwordx4 v[130:133], v[66:67], off
	global_load_dwordx4 v[134:137], v[66:67], off offset:64
	v_mov_b32_e32 v66, s7
	v_mov_b32_e32 v67, s6
	v_lshl_or_b32 v0, v69, 3, v0
	v_lshl_add_u64 v[66:67], v[0:1], 1, v[66:67]
	s_lshl_b32 s80, s42, 7
	v_lshl_add_u64 v[68:69], v[66:67], 0, s[80:81]
	global_load_dwordx4 v[138:141], v[66:67], off
	global_load_dwordx4 v[142:145], v[68:69], off
	v_readlane_b32 s76, v252, 59
	v_readlane_b32 s77, v252, 60

.LBB0_546:
	s_setprio 1
	ds_read_b128 v[238:241], v183
	ds_read_b128 v[242:245], v183 offset:32
	ds_read_b128 v[246:249], v183 offset:64
	ds_read_b128 v[186:189], v183 offset:96
	s_waitcnt lgkmcnt(3)
	v_mfma_f32_32x32x16_bf16 v[82:97], v[238:241], v[98:101], 0
	ds_read_b128 v[238:241], v183 offset:128
	s_waitcnt lgkmcnt(3)
	v_mfma_f32_32x32x16_bf16 v[82:97], v[242:245], v[102:105], v[82:97]
	ds_read_b128 v[242:245], v183 offset:160
	s_waitcnt lgkmcnt(3)
	v_mfma_f32_32x32x16_bf16 v[82:97], v[246:249], v[106:109], v[82:97]
	ds_read_b128 v[246:249], v183 offset:192
	s_waitcnt lgkmcnt(3)
	v_mfma_f32_32x32x16_bf16 v[82:97], v[186:189], v[110:113], v[82:97]
	ds_read_b128 v[186:189], v183 offset:224
	s_waitcnt lgkmcnt(3)
	v_mfma_f32_32x32x16_bf16 v[82:97], v[238:241], v[126:129], v[82:97]
	ds_read_b128 v[238:241], v183 offset:8704
	s_waitcnt lgkmcnt(3)
	v_mfma_f32_32x32x16_bf16 v[82:97], v[242:245], v[114:117], v[82:97]
	ds_read_b128 v[242:245], v183 offset:8736
	s_waitcnt lgkmcnt(3)
	v_mfma_f32_32x32x16_bf16 v[82:97], v[246:249], v[122:125], v[82:97]
	ds_read_b128 v[246:249], v183 offset:8768
	s_waitcnt lgkmcnt(3)
	v_mfma_f32_32x32x16_bf16 v[82:97], v[186:189], v[118:121], v[82:97]
	ds_read_b128 v[186:189], v183 offset:8800
	s_waitcnt lgkmcnt(3)
	v_mfma_f32_32x32x16_bf16 v[66:81], v[238:241], v[98:101], 0
	ds_read_b128 v[238:241], v183 offset:8832
	s_waitcnt lgkmcnt(3)
	v_mfma_f32_32x32x16_bf16 v[66:81], v[242:245], v[102:105], v[66:81]
	ds_read_b128 v[242:245], v183 offset:8864
	s_waitcnt lgkmcnt(3)
	v_mfma_f32_32x32x16_bf16 v[66:81], v[246:249], v[106:109], v[66:81]
	ds_read_b128 v[246:249], v183 offset:8896
	s_waitcnt lgkmcnt(3)
	v_mfma_f32_32x32x16_bf16 v[66:81], v[186:189], v[110:113], v[66:81]
	ds_read_b128 v[186:189], v183 offset:8928
	s_waitcnt lgkmcnt(3)
	v_mfma_f32_32x32x16_bf16 v[66:81], v[238:241], v[126:129], v[66:81]
	s_waitcnt lgkmcnt(2)
	v_mfma_f32_32x32x16_bf16 v[66:81], v[242:245], v[114:117], v[66:81]
	s_waitcnt lgkmcnt(1)
	v_mfma_f32_32x32x16_bf16 v[66:81], v[246:249], v[122:125], v[66:81]
	s_waitcnt lgkmcnt(0)
	v_mfma_f32_32x32x16_bf16 v[66:81], v[186:189], v[118:121], v[66:81]
	s_setprio 0
	v_add_u32_e32 v0, s9, v148
	v_sub_u32_e32 v186, v150, v0
	v_cmp_gt_u32_e32 vcc, s89, v186
	v_mul_f32_e32 v82, 0x3e0293ee, v82
	s_and_b64 vcc, s[38:39], vcc
	v_sub_u32_e32 v186, v0, v150
	v_cndmask_b32_e32 v82, v82, v226, vcc
	v_cmp_lt_u32_e32 vcc, s59, v186
	v_mul_f32_e32 v83, 0x3e0293ee, v83
	s_and_b64 vcc, s[38:39], vcc
	v_sub_u32_e32 v187, v151, v0
	v_cndmask_b32_e32 v83, v83, v226, vcc
	v_cmp_gt_u32_e32 vcc, s89, v187
	v_mul_f32_e32 v84, 0x3e0293ee, v84
	s_and_b64 vcc, s[38:39], vcc
	v_sub_u32_e32 v187, v152, v0
	v_cndmask_b32_e32 v84, v84, v226, vcc
	v_cmp_gt_u32_e32 vcc, s89, v187
	v_mul_f32_e32 v85, 0x3e0293ee, v85
	s_and_b64 vcc, s[38:39], vcc
	v_sub_u32_e32 v187, v153, v0
	v_cndmask_b32_e32 v85, v85, v226, vcc
	v_cmp_gt_u32_e32 vcc, s89, v187
	v_mul_f32_e32 v86, 0x3e0293ee, v86
	s_and_b64 vcc, s[38:39], vcc
	v_sub_u32_e32 v187, v154, v0
	v_cndmask_b32_e32 v86, v86, v226, vcc
	v_cmp_gt_u32_e32 vcc, s89, v187
	v_mul_f32_e32 v87, 0x3e0293ee, v87
	s_and_b64 vcc, s[38:39], vcc
	v_sub_u32_e32 v187, v155, v0
	v_cndmask_b32_e32 v87, v87, v226, vcc
	v_cmp_gt_u32_e32 vcc, s89, v187
	v_mul_f32_e32 v88, 0x3e0293ee, v88
	s_and_b64 vcc, s[38:39], vcc
	v_sub_u32_e32 v187, v156, v0
	v_cndmask_b32_e32 v88, v88, v226, vcc
	v_cmp_gt_u32_e32 vcc, s89, v187
	v_mul_f32_e32 v89, 0x3e0293ee, v89
	s_and_b64 vcc, s[38:39], vcc
	v_sub_u32_e32 v187, v157, v0
	v_cndmask_b32_e32 v89, v89, v226, vcc
	v_cmp_gt_u32_e32 vcc, s89, v187
	v_mul_f32_e32 v90, 0x3e0293ee, v90
	s_and_b64 vcc, s[38:39], vcc
	v_sub_u32_e32 v187, v158, v0
	v_cndmask_b32_e32 v90, v90, v226, vcc
	v_cmp_gt_u32_e32 vcc, s89, v187
	v_mul_f32_e32 v91, 0x3e0293ee, v91
	s_and_b64 vcc, s[38:39], vcc
	v_sub_u32_e32 v187, v159, v0
	v_cndmask_b32_e32 v91, v91, v226, vcc
	v_cmp_gt_u32_e32 vcc, s89, v187
	v_mul_f32_e32 v92, 0x3e0293ee, v92
	s_and_b64 vcc, s[38:39], vcc
	v_sub_u32_e32 v187, v160, v0
	v_cndmask_b32_e32 v92, v92, v226, vcc
	v_cmp_gt_u32_e32 vcc, s89, v187
	v_mul_f32_e32 v93, 0x3e0293ee, v93
	s_and_b64 vcc, s[38:39], vcc
	v_sub_u32_e32 v187, v161, v0
	v_cndmask_b32_e32 v93, v93, v226, vcc
	v_cmp_gt_u32_e32 vcc, s89, v187
	v_mul_f32_e32 v94, 0x3e0293ee, v94
	s_and_b64 vcc, s[38:39], vcc
	v_sub_u32_e32 v187, v162, v0
	v_cndmask_b32_e32 v94, v94, v226, vcc
	v_cmp_gt_u32_e32 vcc, s89, v187
	v_mul_f32_e32 v95, 0x3e0293ee, v95
	s_and_b64 vcc, s[38:39], vcc
	v_sub_u32_e32 v187, v163, v0
	v_cndmask_b32_e32 v95, v95, v226, vcc
	v_cmp_gt_u32_e32 vcc, s89, v187
	s_mov_b32 s6, 0xff61b1e6
	v_mul_f32_e32 v96, 0x3e0293ee, v96
	s_and_b64 vcc, s[38:39], vcc
	v_sub_u32_e32 v187, v164, v0
	v_max3_f32 v186, v82, s6, v83
	v_cndmask_b32_e32 v96, v96, v226, vcc
	v_cmp_gt_u32_e32 vcc, s89, v187
	v_max3_f32 v186, v186, v84, v85
	v_mul_f32_e32 v97, 0x3e0293ee, v97
	s_and_b64 vcc, s[38:39], vcc
	v_sub_u32_e32 v187, v165, v0
	v_max3_f32 v186, v186, v86, v87
	v_cndmask_b32_e32 v97, v97, v226, vcc
	v_cmp_gt_u32_e32 vcc, s89, v187
	v_max3_f32 v186, v186, v88, v89
	v_mul_f32_e32 v66, 0x3e0293ee, v66
	s_and_b64 vcc, s[38:39], vcc
	v_max3_f32 v186, v186, v90, v91
	v_cndmask_b32_e32 v187, v66, v226, vcc
	v_mul_f32_e32 v66, 0x3e0293ee, v67
	v_sub_u32_e32 v67, v166, v0
	v_max3_f32 v186, v186, v92, v93
	v_cmp_gt_u32_e32 vcc, s89, v67
	v_max3_f32 v186, v186, v94, v95
	s_and_b64 vcc, s[38:39], vcc
	v_max3_f32 v186, v186, v96, v97
	v_cndmask_b32_e32 v67, v66, v226, vcc
	v_max3_f32 v66, v186, v187, v67
	v_sub_u32_e32 v186, v167, v0
	v_cmp_gt_u32_e32 vcc, s89, v186
	v_mul_f32_e32 v68, 0x3e0293ee, v68
	s_and_b64 vcc, s[38:39], vcc
	v_sub_u32_e32 v186, v168, v0
	v_cndmask_b32_e32 v68, v68, v226, vcc
	v_cmp_gt_u32_e32 vcc, s89, v186
	v_mul_f32_e32 v69, 0x3e0293ee, v69
	s_and_b64 vcc, s[38:39], vcc
	v_sub_u32_e32 v186, v169, v0
	v_cndmask_b32_e32 v69, v69, v226, vcc
	v_cmp_gt_u32_e32 vcc, s89, v186
	v_mul_f32_e32 v70, 0x3e0293ee, v70
	s_and_b64 vcc, s[38:39], vcc
	v_sub_u32_e32 v186, v170, v0
	v_cndmask_b32_e32 v70, v70, v226, vcc
	v_cmp_gt_u32_e32 vcc, s89, v186
	v_mul_f32_e32 v71, 0x3e0293ee, v71
	s_and_b64 vcc, s[38:39], vcc
	v_sub_u32_e32 v186, v171, v0
	v_cndmask_b32_e32 v71, v71, v226, vcc
	v_cmp_gt_u32_e32 vcc, s89, v186
	v_mul_f32_e32 v72, 0x3e0293ee, v72
	s_and_b64 vcc, s[38:39], vcc
	v_sub_u32_e32 v186, v172, v0
	v_cndmask_b32_e32 v72, v72, v226, vcc
	v_cmp_gt_u32_e32 vcc, s89, v186
	v_mul_f32_e32 v73, 0x3e0293ee, v73
	s_and_b64 vcc, s[38:39], vcc
	v_sub_u32_e32 v186, v173, v0
	v_cndmask_b32_e32 v73, v73, v226, vcc
	v_cmp_gt_u32_e32 vcc, s89, v186
	v_mul_f32_e32 v74, 0x3e0293ee, v74
	s_and_b64 vcc, s[38:39], vcc
	v_sub_u32_e32 v186, v174, v0
	v_cndmask_b32_e32 v74, v74, v226, vcc
	v_cmp_gt_u32_e32 vcc, s89, v186
	v_mul_f32_e32 v75, 0x3e0293ee, v75
	s_and_b64 vcc, s[38:39], vcc
	v_sub_u32_e32 v186, v175, v0
	v_cndmask_b32_e32 v75, v75, v226, vcc
	v_cmp_gt_u32_e32 vcc, s89, v186
	v_mul_f32_e32 v76, 0x3e0293ee, v76
	s_and_b64 vcc, s[38:39], vcc
	v_sub_u32_e32 v186, v176, v0
	v_cndmask_b32_e32 v76, v76, v226, vcc
	v_cmp_gt_u32_e32 vcc, s89, v186
	v_mul_f32_e32 v77, 0x3e0293ee, v77
	s_and_b64 vcc, s[38:39], vcc
	v_sub_u32_e32 v186, v177, v0
	v_cndmask_b32_e32 v77, v77, v226, vcc
	v_cmp_gt_u32_e32 vcc, s89, v186
	v_mul_f32_e32 v78, 0x3e0293ee, v78
	s_and_b64 vcc, s[38:39], vcc
	v_sub_u32_e32 v186, v178, v0
	v_cndmask_b32_e32 v78, v78, v226, vcc
	v_cmp_gt_u32_e32 vcc, s89, v186
	v_mul_f32_e32 v79, 0x3e0293ee, v79
	s_and_b64 vcc, s[38:39], vcc
	v_sub_u32_e32 v186, v179, v0
	v_cndmask_b32_e32 v79, v79, v226, vcc
	v_cmp_gt_u32_e32 vcc, s89, v186
	v_max3_f32 v66, v66, v68, v69
	v_mul_f32_e32 v80, 0x3e0293ee, v80
	s_and_b64 vcc, s[38:39], vcc
	v_sub_u32_e32 v0, v180, v0
	v_max3_f32 v66, v66, v70, v71
	v_cndmask_b32_e32 v80, v80, v226, vcc
	v_cmp_gt_u32_e32 vcc, s89, v0
	v_max3_f32 v66, v66, v72, v73
	v_mul_f32_e32 v81, 0x3e0293ee, v81
	s_and_b64 vcc, s[38:39], vcc
	v_and_b32_e32 v186, 64, v223
	v_max3_f32 v66, v66, v74, v75
	v_cndmask_b32_e32 v0, v81, v226, vcc
	v_xor_b32_e32 v81, 32, v223
	v_add_u32_e32 v186, 64, v186
	v_max3_f32 v66, v66, v76, v77
	v_cmp_lt_i32_e32 vcc, v81, v186
	v_max3_f32 v66, v66, v78, v79
	v_max3_f32 v66, v66, v80, v0
	v_cndmask_b32_e32 v81, v223, v81, vcc
	v_lshlrev_b32_e32 v81, 2, v81
	ds_bpermute_b32 v186, v81, v66
	s_waitcnt lgkmcnt(0)
	v_max3_f32 v66, v185, v66, v186
	v_sub_f32_e32 v82, v82, v66
	v_exp_f32_e32 v82, v82
	v_sub_f32_e32 v83, v83, v66
	v_exp_f32_e32 v83, v83
	v_sub_f32_e32 v84, v84, v66
	v_exp_f32_e32 v84, v84
	v_sub_f32_e32 v85, v85, v66
	v_exp_f32_e32 v85, v85
	v_sub_f32_e32 v86, v86, v66
	v_add_f32_e32 v186, 0, v82
	v_exp_f32_e32 v86, v86
	v_sub_f32_e32 v87, v87, v66
	v_add_f32_e32 v186, v83, v186
	v_exp_f32_e32 v87, v87
	v_sub_f32_e32 v88, v88, v66
	v_add_f32_e32 v186, v84, v186
	v_exp_f32_e32 v88, v88
	v_sub_f32_e32 v89, v89, v66
	v_add_f32_e32 v186, v85, v186
	v_exp_f32_e32 v89, v89
	v_sub_f32_e32 v90, v90, v66
	v_add_f32_e32 v186, v86, v186
	v_exp_f32_e32 v90, v90
	v_sub_f32_e32 v91, v91, v66
	v_add_f32_e32 v186, v87, v186
	v_exp_f32_e32 v91, v91
	v_sub_f32_e32 v92, v92, v66
	v_add_f32_e32 v186, v88, v186
	v_exp_f32_e32 v92, v92
	v_sub_f32_e32 v93, v93, v66
	v_add_f32_e32 v186, v89, v186
	v_exp_f32_e32 v93, v93
	v_sub_f32_e32 v94, v94, v66
	v_add_f32_e32 v186, v90, v186
	v_exp_f32_e32 v94, v94
	v_sub_f32_e32 v95, v95, v66
	v_add_f32_e32 v186, v91, v186
	v_exp_f32_e32 v95, v95
	v_sub_f32_e32 v96, v96, v66
	v_add_f32_e32 v186, v92, v186
	v_exp_f32_e32 v96, v96
	v_sub_f32_e32 v97, v97, v66
	v_add_f32_e32 v186, v93, v186
	v_exp_f32_e32 v97, v97
	v_sub_f32_e32 v187, v187, v66
	v_add_f32_e32 v186, v94, v186
	v_exp_f32_e32 v187, v187
	v_sub_f32_e32 v67, v67, v66
	v_add_f32_e32 v186, v95, v186
	v_exp_f32_e32 v67, v67
	v_sub_f32_e32 v68, v68, v66
	v_add_f32_e32 v186, v96, v186
	v_exp_f32_e32 v188, v68
	v_sub_f32_e32 v68, v69, v66
	v_add_f32_e32 v186, v97, v186
	v_exp_f32_e32 v189, v68
	v_sub_f32_e32 v68, v70, v66
	v_add_f32_e32 v186, v187, v186
	v_exp_f32_e32 v190, v68
	v_sub_f32_e32 v69, v71, v66
	v_add_f32_e32 v68, v67, v186
	v_exp_f32_e32 v186, v69
	v_sub_f32_e32 v69, v72, v66
	v_add_f32_e32 v68, v188, v68
	v_exp_f32_e32 v191, v69
	v_sub_f32_e32 v69, v73, v66
	v_add_f32_e32 v68, v189, v68
	v_exp_f32_e32 v192, v69
	v_sub_f32_e32 v69, v74, v66
	v_add_f32_e32 v68, v190, v68
	v_exp_f32_e32 v193, v69
	v_sub_f32_e32 v69, v75, v66
	v_add_f32_e32 v68, v186, v68
	v_exp_f32_e32 v194, v69
	v_sub_f32_e32 v69, v76, v66
	v_add_f32_e32 v68, v191, v68
	v_exp_f32_e32 v76, v69
	v_sub_f32_e32 v69, v77, v66
	v_add_f32_e32 v68, v192, v68
	v_exp_f32_e32 v77, v69
	v_sub_f32_e32 v69, v78, v66
	v_add_f32_e32 v68, v193, v68
	v_exp_f32_e32 v78, v69
	v_sub_f32_e32 v69, v79, v66
	v_add_f32_e32 v68, v194, v68
	v_exp_f32_e32 v79, v69
	v_sub_f32_e32 v69, v80, v66
	v_add_f32_e32 v68, v76, v68
	v_exp_f32_e32 v80, v69
	v_sub_f32_e32 v0, v0, v66
	v_add_f32_e32 v68, v77, v68
	v_exp_f32_e32 v195, v0
	v_add_f32_e32 v68, v78, v68
	v_add_f32_e32 v68, v79, v68
	v_add_f32_e32 v68, v80, v68
	v_sub_f32_e32 v185, v185, v66
	v_add_f32_e32 v68, v195, v68
	v_exp_f32_e32 v0, v185
	ds_bpermute_b32 v69, v81, v68
	v_pk_mul_f32 v[64:65], v[64:65], v[0:1] op_sel_hi:[1,0]
	v_pk_mul_f32 v[62:63], v[62:63], v[0:1] op_sel_hi:[1,0]
	v_pk_mul_f32 v[60:61], v[60:61], v[0:1] op_sel_hi:[1,0]
	v_pk_mul_f32 v[58:59], v[58:59], v[0:1] op_sel_hi:[1,0]
	v_pk_mul_f32 v[56:57], v[56:57], v[0:1] op_sel_hi:[1,0]
	v_pk_mul_f32 v[54:55], v[54:55], v[0:1] op_sel_hi:[1,0]
	v_pk_mul_f32 v[52:53], v[52:53], v[0:1] op_sel_hi:[1,0]
	v_pk_mul_f32 v[50:51], v[50:51], v[0:1] op_sel_hi:[1,0]
	v_pk_mul_f32 v[48:49], v[48:49], v[0:1] op_sel_hi:[1,0]
	v_pk_mul_f32 v[46:47], v[46:47], v[0:1] op_sel_hi:[1,0]
	v_pk_mul_f32 v[44:45], v[44:45], v[0:1] op_sel_hi:[1,0]
	v_pk_mul_f32 v[42:43], v[42:43], v[0:1] op_sel_hi:[1,0]
	v_pk_mul_f32 v[40:41], v[40:41], v[0:1] op_sel_hi:[1,0]
	v_pk_mul_f32 v[38:39], v[38:39], v[0:1] op_sel_hi:[1,0]
	v_pk_mul_f32 v[36:37], v[36:37], v[0:1] op_sel_hi:[1,0]
	v_pk_mul_f32 v[34:35], v[34:35], v[0:1] op_sel_hi:[1,0]
	v_pk_mul_f32 v[32:33], v[32:33], v[0:1] op_sel_hi:[1,0]
	v_pk_mul_f32 v[30:31], v[30:31], v[0:1] op_sel_hi:[1,0]
	v_pk_mul_f32 v[28:29], v[28:29], v[0:1] op_sel_hi:[1,0]
	v_pk_mul_f32 v[26:27], v[26:27], v[0:1] op_sel_hi:[1,0]
	v_pk_mul_f32 v[24:25], v[24:25], v[0:1] op_sel_hi:[1,0]
	v_pk_mul_f32 v[22:23], v[22:23], v[0:1] op_sel_hi:[1,0]
	v_pk_mul_f32 v[20:21], v[20:21], v[0:1] op_sel_hi:[1,0]
	v_pk_mul_f32 v[18:19], v[18:19], v[0:1] op_sel_hi:[1,0]
	v_pk_mul_f32 v[16:17], v[16:17], v[0:1] op_sel_hi:[1,0]
	v_pk_mul_f32 v[14:15], v[14:15], v[0:1] op_sel_hi:[1,0]
	v_pk_mul_f32 v[12:13], v[12:13], v[0:1] op_sel_hi:[1,0]
	v_pk_mul_f32 v[10:11], v[10:11], v[0:1] op_sel_hi:[1,0]
	v_pk_mul_f32 v[8:9], v[8:9], v[0:1] op_sel_hi:[1,0]
	v_pk_mul_f32 v[6:7], v[6:7], v[0:1] op_sel_hi:[1,0]
	v_pk_mul_f32 v[4:5], v[4:5], v[0:1] op_sel_hi:[1,0]
	v_pk_mul_f32 v[2:3], v[2:3], v[0:1] op_sel_hi:[1,0]
	s_waitcnt lgkmcnt(0)
	v_add_f32_e32 v81, v68, v69
	s_setprio 1
	v_cvt_pk_bf16_f32 v68, v82, v83
	v_cvt_pk_bf16_f32 v69, v84, v85
	v_cvt_pk_bf16_f32 v70, v86, v87
	v_cvt_pk_bf16_f32 v71, v88, v89
	v_add_u32_e32 v82, 0x4000, v184
	v_add_u32_e32 v83, 0x5000, v184
	v_add_u32_e32 v84, 0x6800, v184
	v_add_u32_e32 v85, 0x7800, v184
	ds_read2_b64 v[72:75], v82 offset0:128 offset1:130
	ds_read2_b64 v[238:241], v83 offset0:192 offset1:194
	ds_read2_b64 v[242:245], v84 offset1:2
	ds_read2_b64 v[246:249], v85 offset0:64 offset1:66
	s_waitcnt lgkmcnt(3)
	s_nop 0
	v_mfma_f32_32x32x16_bf16 v[50:65], v[72:75], v[68:71], v[50:65]
	ds_read2_b64 v[72:75], v82 offset0:132 offset1:134
	s_waitcnt lgkmcnt(3)
	v_mfma_f32_32x32x16_bf16 v[34:49], v[238:241], v[68:71], v[34:49]
	ds_read2_b64 v[238:241], v83 offset0:196 offset1:198
	s_waitcnt lgkmcnt(3)
	v_mfma_f32_32x32x16_bf16 v[18:33], v[242:245], v[68:71], v[18:33]
	ds_read2_b64 v[242:245], v84 offset0:4 offset1:6
	s_waitcnt lgkmcnt(3)
	v_mfma_f32_32x32x16_bf16 v[2:17], v[246:249], v[68:71], v[2:17]
	ds_read2_b64 v[246:249], v85 offset0:68 offset1:70
	v_cvt_pk_bf16_f32 v68, v90, v91
	v_cvt_pk_bf16_f32 v69, v92, v93
	v_cvt_pk_bf16_f32 v70, v94, v95
	v_cvt_pk_bf16_f32 v71, v96, v97
	s_waitcnt lgkmcnt(3)
	s_nop 0
	v_mfma_f32_32x32x16_bf16 v[50:65], v[72:75], v[68:71], v[50:65]
	ds_read2_b64 v[72:75], v82 offset0:136 offset1:138
	s_waitcnt lgkmcnt(3)
	v_mfma_f32_32x32x16_bf16 v[34:49], v[238:241], v[68:71], v[34:49]
	ds_read2_b64 v[238:241], v83 offset0:200 offset1:202
	s_waitcnt lgkmcnt(3)
	v_mfma_f32_32x32x16_bf16 v[18:33], v[242:245], v[68:71], v[18:33]
	ds_read2_b64 v[242:245], v84 offset0:8 offset1:10
	s_waitcnt lgkmcnt(3)
	v_mfma_f32_32x32x16_bf16 v[2:17], v[246:249], v[68:71], v[2:17]
	ds_read2_b64 v[246:249], v85 offset0:72 offset1:74
	v_cvt_pk_bf16_f32 v68, v187, v67
	v_cvt_pk_bf16_f32 v69, v188, v189
	v_cvt_pk_bf16_f32 v70, v190, v186
	v_cvt_pk_bf16_f32 v71, v191, v192
	s_waitcnt lgkmcnt(3)
	s_nop 0
	v_mfma_f32_32x32x16_bf16 v[50:65], v[72:75], v[68:71], v[50:65]
	ds_read2_b64 v[72:75], v82 offset0:140 offset1:142
	s_waitcnt lgkmcnt(3)
	v_mfma_f32_32x32x16_bf16 v[34:49], v[238:241], v[68:71], v[34:49]
	ds_read2_b64 v[238:241], v83 offset0:204 offset1:206
	s_waitcnt lgkmcnt(3)
	v_mfma_f32_32x32x16_bf16 v[18:33], v[242:245], v[68:71], v[18:33]
	ds_read2_b64 v[242:245], v84 offset0:12 offset1:14
	s_waitcnt lgkmcnt(3)
	v_mfma_f32_32x32x16_bf16 v[2:17], v[246:249], v[68:71], v[2:17]
	ds_read2_b64 v[246:249], v85 offset0:76 offset1:78
	v_cvt_pk_bf16_f32 v68, v193, v194
	v_cvt_pk_bf16_f32 v69, v76, v77
	v_cvt_pk_bf16_f32 v70, v78, v79
	v_cvt_pk_bf16_f32 v71, v80, v195
	s_waitcnt lgkmcnt(3)
	s_nop 0
	v_mfma_f32_32x32x16_bf16 v[50:65], v[72:75], v[68:71], v[50:65]
	s_waitcnt lgkmcnt(2)
	v_mfma_f32_32x32x16_bf16 v[34:49], v[238:241], v[68:71], v[34:49]
	s_waitcnt lgkmcnt(1)
	v_mfma_f32_32x32x16_bf16 v[18:33], v[242:245], v[68:71], v[18:33]
	s_waitcnt lgkmcnt(0)
	v_mfma_f32_32x32x16_bf16 v[2:17], v[246:249], v[68:71], v[2:17]
	v_fmac_f32_e32 v81, v149, v0
	s_setprio 0
	v_mov_b32_e32 v149, v81
	v_mov_b32_e32 v185, v66
	s_add_i32 s68, s68, 64
	s_cmp_lg_u32 s71, s8
	s_cbranch_scc0 .LBB0_476
